# prenorm 11-slice context partial sums: rolling 4-slice load pipeline instead of three drained batches
# baseline (speedup 1.0000x reference)
.LBB0_429:
	s_andn2_b64 vcc, exec, s[8:9]
	s_cbranch_vccnz .LBB0_434
	s_cmpk_lt_i32 s3, 0x4000
	s_cbranch_scc1 .LBB0_432
	s_lshl_b64 s[8:9], s[74:75], 12
	v_lshl_add_u64 v[48:49], v[36:37], 0, s[8:9]
	global_load_dwordx4 v[54:57], v[48:49], off
	global_load_dwordx4 v[58:61], v[48:49], off offset:1024
	global_load_dwordx4 v[62:65], v[48:49], off offset:2048
	global_load_dwordx4 v[66:69], v[48:49], off offset:3072
	s_mov_b32 s5, 0x400000
	v_add_co_u32_e32 v50, vcc, s5, v48
	s_nop 1
	v_addc_co_u32_e32 v51, vcc, 0, v49, vcc
	global_load_dwordx4 v[70:73], v[50:51], off
	global_load_dwordx4 v[74:77], v[50:51], off offset:1024
	global_load_dwordx4 v[78:81], v[50:51], off offset:2048
	global_load_dwordx4 v[82:85], v[50:51], off offset:3072
	s_mov_b32 s5, 0x800000
	v_add_co_u32_e32 v50, vcc, s5, v48
	s_nop 1
	v_addc_co_u32_e32 v51, vcc, 0, v49, vcc
	global_load_dwordx4 v[86:89], v[50:51], off
	global_load_dwordx4 v[90:93], v[50:51], off offset:1024
	global_load_dwordx4 v[94:97], v[50:51], off offset:2048
	global_load_dwordx4 v[98:101], v[50:51], off offset:3072
	s_mov_b32 s5, 0xc00000
	v_add_co_u32_e32 v50, vcc, s5, v48
	s_nop 1
	v_addc_co_u32_e32 v51, vcc, 0, v49, vcc
	global_load_dwordx4 v[102:105], v[50:51], off
	global_load_dwordx4 v[106:109], v[50:51], off offset:1024
	global_load_dwordx4 v[110:113], v[50:51], off offset:2048
	global_load_dwordx4 v[114:117], v[50:51], off offset:3072
	s_waitcnt vmcnt(12)
	v_pk_add_f32 v[30:31], v[30:31], v[54:55]
	v_pk_add_f32 v[32:33], v[32:33], v[56:57]
	v_pk_add_f32 v[22:23], v[22:23], v[58:59]
	v_pk_add_f32 v[24:25], v[24:25], v[60:61]
	v_pk_add_f32 v[14:15], v[14:15], v[62:63]
	v_pk_add_f32 v[16:17], v[16:17], v[64:65]
	v_pk_add_f32 v[6:7], v[6:7], v[66:67]
	v_pk_add_f32 v[8:9], v[8:9], v[68:69]
	s_mov_b32 s5, 0x1000000
	v_add_co_u32_e32 v50, vcc, s5, v48
	s_nop 1
	v_addc_co_u32_e32 v51, vcc, 0, v49, vcc
	global_load_dwordx4 v[54:57], v[50:51], off
	global_load_dwordx4 v[58:61], v[50:51], off offset:1024
	global_load_dwordx4 v[62:65], v[50:51], off offset:2048
	global_load_dwordx4 v[66:69], v[50:51], off offset:3072
	s_waitcnt vmcnt(12)
	v_pk_add_f32 v[30:31], v[30:31], v[70:71]
	v_pk_add_f32 v[32:33], v[32:33], v[72:73]
	v_pk_add_f32 v[22:23], v[22:23], v[74:75]
	v_pk_add_f32 v[24:25], v[24:25], v[76:77]
	v_pk_add_f32 v[14:15], v[14:15], v[78:79]
	v_pk_add_f32 v[16:17], v[16:17], v[80:81]
	v_pk_add_f32 v[6:7], v[6:7], v[82:83]
	v_pk_add_f32 v[8:9], v[8:9], v[84:85]
	s_mov_b32 s5, 0x1400000
	v_add_co_u32_e32 v50, vcc, s5, v48
	s_nop 1
	v_addc_co_u32_e32 v51, vcc, 0, v49, vcc
	global_load_dwordx4 v[70:73], v[50:51], off
	global_load_dwordx4 v[74:77], v[50:51], off offset:1024
	global_load_dwordx4 v[78:81], v[50:51], off offset:2048
	global_load_dwordx4 v[82:85], v[50:51], off offset:3072
	s_waitcnt vmcnt(12)
	v_pk_add_f32 v[30:31], v[30:31], v[86:87]
	v_pk_add_f32 v[32:33], v[32:33], v[88:89]
	v_pk_add_f32 v[22:23], v[22:23], v[90:91]
	v_pk_add_f32 v[24:25], v[24:25], v[92:93]
	v_pk_add_f32 v[14:15], v[14:15], v[94:95]
	v_pk_add_f32 v[16:17], v[16:17], v[96:97]
	v_pk_add_f32 v[6:7], v[6:7], v[98:99]
	v_pk_add_f32 v[8:9], v[8:9], v[100:101]
	s_mov_b32 s5, 0x1800000
	v_add_co_u32_e32 v50, vcc, s5, v48
	s_nop 1
	v_addc_co_u32_e32 v51, vcc, 0, v49, vcc
	global_load_dwordx4 v[86:89], v[50:51], off
	global_load_dwordx4 v[90:93], v[50:51], off offset:1024
	global_load_dwordx4 v[94:97], v[50:51], off offset:2048
	global_load_dwordx4 v[98:101], v[50:51], off offset:3072
	s_waitcnt vmcnt(12)
	v_pk_add_f32 v[30:31], v[30:31], v[102:103]
	v_pk_add_f32 v[32:33], v[32:33], v[104:105]
	v_pk_add_f32 v[22:23], v[22:23], v[106:107]
	v_pk_add_f32 v[24:25], v[24:25], v[108:109]
	v_pk_add_f32 v[14:15], v[14:15], v[110:111]
	v_pk_add_f32 v[16:17], v[16:17], v[112:113]
	v_pk_add_f32 v[6:7], v[6:7], v[114:115]
	v_pk_add_f32 v[8:9], v[8:9], v[116:117]
	s_mov_b32 s5, 0x1c00000
	v_add_co_u32_e32 v50, vcc, s5, v48
	s_nop 1
	v_addc_co_u32_e32 v51, vcc, 0, v49, vcc
	global_load_dwordx4 v[102:105], v[50:51], off
	global_load_dwordx4 v[106:109], v[50:51], off offset:1024
	global_load_dwordx4 v[110:113], v[50:51], off offset:2048
	global_load_dwordx4 v[114:117], v[50:51], off offset:3072
	s_waitcnt vmcnt(12)
	v_pk_add_f32 v[30:31], v[30:31], v[54:55]
	v_pk_add_f32 v[32:33], v[32:33], v[56:57]
	v_pk_add_f32 v[22:23], v[22:23], v[58:59]
	v_pk_add_f32 v[24:25], v[24:25], v[60:61]
	v_pk_add_f32 v[14:15], v[14:15], v[62:63]
	v_pk_add_f32 v[16:17], v[16:17], v[64:65]
	v_pk_add_f32 v[6:7], v[6:7], v[66:67]
	v_pk_add_f32 v[8:9], v[8:9], v[68:69]
	s_mov_b32 s5, 0x2000000
	v_add_co_u32_e32 v50, vcc, s5, v48
	s_nop 1
	v_addc_co_u32_e32 v51, vcc, 0, v49, vcc
	global_load_dwordx4 v[54:57], v[50:51], off
	global_load_dwordx4 v[58:61], v[50:51], off offset:1024
	global_load_dwordx4 v[62:65], v[50:51], off offset:2048
	global_load_dwordx4 v[66:69], v[50:51], off offset:3072
	s_waitcnt vmcnt(12)
	v_pk_add_f32 v[30:31], v[30:31], v[70:71]
	v_pk_add_f32 v[32:33], v[32:33], v[72:73]
	v_pk_add_f32 v[22:23], v[22:23], v[74:75]
	v_pk_add_f32 v[24:25], v[24:25], v[76:77]
	v_pk_add_f32 v[14:15], v[14:15], v[78:79]
	v_pk_add_f32 v[16:17], v[16:17], v[80:81]
	v_pk_add_f32 v[6:7], v[6:7], v[82:83]
	v_pk_add_f32 v[8:9], v[8:9], v[84:85]
	s_mov_b32 s5, 0x2400000
	v_add_co_u32_e32 v50, vcc, s5, v48
	s_nop 1
	v_addc_co_u32_e32 v51, vcc, 0, v49, vcc
	global_load_dwordx4 v[70:73], v[50:51], off
	global_load_dwordx4 v[74:77], v[50:51], off offset:1024
	global_load_dwordx4 v[78:81], v[50:51], off offset:2048
	global_load_dwordx4 v[82:85], v[50:51], off offset:3072
	s_waitcnt vmcnt(12)
	v_pk_add_f32 v[30:31], v[30:31], v[86:87]
	v_pk_add_f32 v[32:33], v[32:33], v[88:89]
	v_pk_add_f32 v[22:23], v[22:23], v[90:91]
	v_pk_add_f32 v[24:25], v[24:25], v[92:93]
	v_pk_add_f32 v[14:15], v[14:15], v[94:95]
	v_pk_add_f32 v[16:17], v[16:17], v[96:97]
	v_pk_add_f32 v[6:7], v[6:7], v[98:99]
	v_pk_add_f32 v[8:9], v[8:9], v[100:101]
	s_mov_b32 s5, 0x2800000
	v_add_co_u32_e32 v50, vcc, s5, v48
	s_nop 1
	v_addc_co_u32_e32 v51, vcc, 0, v49, vcc
	global_load_dwordx4 v[86:89], v[50:51], off
	global_load_dwordx4 v[90:93], v[50:51], off offset:1024
	global_load_dwordx4 v[94:97], v[50:51], off offset:2048
	global_load_dwordx4 v[98:101], v[50:51], off offset:3072
	s_waitcnt vmcnt(12)
	v_pk_add_f32 v[30:31], v[30:31], v[102:103]
	v_pk_add_f32 v[32:33], v[32:33], v[104:105]
	v_pk_add_f32 v[22:23], v[22:23], v[106:107]
	v_pk_add_f32 v[24:25], v[24:25], v[108:109]
	v_pk_add_f32 v[14:15], v[14:15], v[110:111]
	v_pk_add_f32 v[16:17], v[16:17], v[112:113]
	v_pk_add_f32 v[6:7], v[6:7], v[114:115]
	v_pk_add_f32 v[8:9], v[8:9], v[116:117]
	s_waitcnt vmcnt(8)
	v_pk_add_f32 v[30:31], v[30:31], v[54:55]
	v_pk_add_f32 v[32:33], v[32:33], v[56:57]
	v_pk_add_f32 v[22:23], v[22:23], v[58:59]
	v_pk_add_f32 v[24:25], v[24:25], v[60:61]
	v_pk_add_f32 v[14:15], v[14:15], v[62:63]
	v_pk_add_f32 v[16:17], v[16:17], v[64:65]
	v_pk_add_f32 v[6:7], v[6:7], v[66:67]
	v_pk_add_f32 v[8:9], v[8:9], v[68:69]
	s_waitcnt vmcnt(4)
	v_pk_add_f32 v[30:31], v[30:31], v[70:71]
	v_pk_add_f32 v[32:33], v[32:33], v[72:73]
	v_pk_add_f32 v[22:23], v[22:23], v[74:75]
	v_pk_add_f32 v[24:25], v[24:25], v[76:77]
	v_pk_add_f32 v[14:15], v[14:15], v[78:79]
	v_pk_add_f32 v[16:17], v[16:17], v[80:81]
	v_pk_add_f32 v[6:7], v[6:7], v[82:83]
	v_pk_add_f32 v[8:9], v[8:9], v[84:85]
	s_waitcnt vmcnt(0)
	v_pk_add_f32 v[30:31], v[30:31], v[86:87]
	v_pk_add_f32 v[32:33], v[32:33], v[88:89]
	v_pk_add_f32 v[22:23], v[22:23], v[90:91]
	v_pk_add_f32 v[24:25], v[24:25], v[92:93]
	v_pk_add_f32 v[14:15], v[14:15], v[94:95]
	v_pk_add_f32 v[16:17], v[16:17], v[96:97]
	v_pk_add_f32 v[6:7], v[6:7], v[98:99]
	v_pk_add_f32 v[8:9], v[8:9], v[100:101]
	v_lshl_add_u64 v[48:49], v[44:45], 0, s[8:9]
	global_store_dwordx4 v[48:49], v[30:33], off
	global_store_dwordx4 v[48:49], v[22:25], off offset:1024
	global_store_dwordx4 v[48:49], v[14:17], off offset:2048
	global_store_dwordx4 v[48:49], v[6:9], off offset:3072
